# one static s_setprio 1 for waves 4-7 at kernel entry (no per-phase flips), on top of ALIGN-barrier removal
# baseline (speedup 1.0000x reference)
; #define LAS __attribute__((address_space(3)))
; __device__ __forceinline__ KArg ka_get() { KArg k = (KArg)__builtin_amdgcn_kernarg_segment_ptr(); asm volatile("" : "+s"(k)); return k; }
; __device__ __forceinline__ unsigned char* ka_ws(KArg k) { return *(unsigned char* const __attribute__((address_space(4)))*)(k + 216); }
; __device__ __forceinline__ unsigned xb_add(unsigned* p, unsigned v) { return __hip_atomic_fetch_add(p, v, __ATOMIC_RELAXED, __HIP_MEMORY_SCOPE_AGENT); }
; __device__ __forceinline__ unsigned xb_xcc_id() { return (unsigned)__builtin_amdgcn_s_getreg((3 << 11) | 20) & 0xFu; }
; __global__ void __launch_bounds__(512, 2) hybrid_fwd(Params Pk) {
;     LAS unsigned char* lds = (LAS unsigned char*)g_lds;
;     cg::grid_group grid = cg::this_grid();
;     if (threadIdx.x < 2) ((LAS unsigned*)(lds + LDS_XB))[threadIdx.x] = 0u;
;     { const KArg P0 = ka_get(); unsigned* bar0 = (unsigned*)(ka_ws(P0) + WS_BAR); if (threadIdx.x == 0) (void)xb_add(&bar0[XB_XCNT(xb_xcc_id())], 1u); }
;     __syncthreads();
;     bool first = true;
;     const int ph_lo = Pk.ph_lo, ph_hi = Pk.ph_hi;
_Z10hybrid_fwd6Params:
	v_and_b32_e32 v155, 0x3ff, v0
	s_nop 0
	v_readfirstlane_b32 s99, v155
	s_nop 3
	s_lshr_b32 s99, s99, 6
	s_cmp_ge_u32 s99, 4
	s_cbranch_scc0 .Lprio_done
	s_setprio 1
.Lprio_done:
	v_writelane_b32 v254, s2, 0
	s_load_dwordx2 s[2:3], s[0:1], 0xe0
	v_cmp_gt_u32_e32 vcc, 2, v155
	s_waitcnt lgkmcnt(0)
	v_writelane_b32 v254, s2, 1
	s_nop 1
	v_writelane_b32 v254, s3, 2
	s_add_u32 s2, s0, 0xe8
	v_writelane_b32 v254, s0, 3
	s_addc_u32 s3, s1, 0
	s_nop 0
	v_writelane_b32 v254, s1, 4
	v_writelane_b32 v254, s2, 5
	s_nop 1
	v_writelane_b32 v254, s3, 6
	s_and_saveexec_b64 s[0:1], vcc
	v_lshl_add_u32 v1, v155, 2, 0
	v_add_u32_e32 v1, 0x23fc8, v1
	v_mov_b32_e32 v2, 0
	ds_write_b32 v1, v2
	s_or_b64 exec, exec, s[0:1]
	v_readlane_b32 s2, v254, 3
	v_readlane_b32 s3, v254, 4
	s_load_dwordx2 s[0:1], s[2:3], 0xe8
	v_cmp_eq_u32_e64 s[4:5], 0, v155
	s_waitcnt lgkmcnt(0)
	v_writelane_b32 v254, s0, 7
	s_nop 1
	v_writelane_b32 v254, s1, 8
	s_mov_b64 s[0:1], exec
	v_writelane_b32 v254, s4, 9
	s_nop 1
	v_writelane_b32 v254, s5, 10
	s_and_b64 s[4:5], s[0:1], s[4:5]
	s_mov_b64 exec, s[4:5]
	s_cbranch_execz .LBB0_5
	s_mov_b64 s[4:5], exec
	v_mbcnt_lo_u32_b32 v1, s4, 0
	v_mbcnt_hi_u32_b32 v1, s5, v1
	v_cmp_eq_u32_e32 vcc, 0, v1
	s_getreg_b32 s6, hwreg(HW_REG_XCC_ID, 0, 4)
	s_and_b64 s[8:9], exec, vcc
	s_mov_b64 exec, s[8:9]
	s_cbranch_execz .LBB0_5
	s_load_dwordx2 s[2:3], s[2:3], 0xd8
	s_lshl_b32 s6, s6, 8
	s_and_b32 s6, s6, 0xf00
	v_mov_b32_e32 v1, 0x3c00000
	s_waitcnt lgkmcnt(0)
	s_add_u32 s2, s2, s6
	s_addc_u32 s3, s3, 0
	s_bcnt1_i32_b64 s4, s[4:5]
	v_mov_b32_e32 v2, s4
	global_atomic_add v1, v2, s[2:3] offset:1024
